# P7 layer-0 EpiRes (from_inputs) epilogue regenerated: two register sets, next row-pair's loads in flight during the current one, counted waits
# baseline (speedup 1.0000x reference)
.LBB0_1079:
	s_ashr_i32 s17, s16, 31
	s_lshl_b64 s[16:17], s[16:17], 19
	s_lshl_b64 s[22:23], s[28:29], 2
	v_mov_b32_e32 v146, v1
	v_lshl_or_b32 v122, s18, 8, v190
	s_add_u32 s22, s77, s22
	s_addc_u32 s23, s78, s23
	v_add_u32_e32 v150, v122, v146
	v_ashrrev_i32_e32 v151, 31, v150
	v_lshl_add_u64 v[126:127], v[150:151], 2, s[22:23]
	global_load_dwordx4 v[130:133], v[126:127], off offset:16
	global_load_dwordx4 v[134:137], v[126:127], off
	global_load_dwordx4 v[122:125], v[126:127], off offset:528
	s_nop 0
	global_load_dwordx4 v[126:129], v[126:127], off offset:512
	v_readlane_b32 s26, v255, 7
	s_add_u32 s22, s88, s16
	v_readlane_b32 s27, v255, 8
	s_addc_u32 s23, s89, s17
	v_add_u32_e32 v146, v146, v188
	s_andn2_b64 vcc, exec, s[26:27]
	v_readlane_b32 s26, v255, 0
	v_readlane_b32 s30, v255, 2
	s_mov_b64 s[16:17], -1
	v_ashrrev_i32_e32 v147, 31, v146
	v_lshl_add_u64 v[148:149], v[150:151], 1, s[22:23]
	v_readlane_b32 s27, v255, 1
	v_readlane_b32 s31, v255, 3
	s_cbranch_vccnz .LBB0_1081
	v_lshl_add_u64 v[150:151], v[150:151], 2, s[20:21]
	v_lshlrev_b64 v[164:165], 12, v[146:147]
	v_lshl_add_u64 v[150:151], v[150:151], 0, v[164:165]
	v_lshlrev_b64 v[164:165], 11, v[146:147]
	v_lshl_add_u64 v[208:209], v[148:149], 0, v[164:165]
	global_load_dwordx4 v[152:155], v[150:151], off offset:16
	global_load_dwordx4 v[156:159], v[150:151], off
	global_load_dwordx4 v[160:163], v[150:151], off offset:528
	global_load_dwordx4 v[176:179], v[150:151], off offset:512
	v_add_co_u32_e32 v164, vcc, 0x10000, v150
	s_nop 1
	v_addc_co_u32_e32 v165, vcc, 0, v151, vcc
	global_load_dwordx4 v[180:183], v[164:165], off offset:16
	global_load_dwordx4 v[184:187], v[164:165], off
	global_load_dwordx4 v[192:195], v[164:165], off offset:528
	global_load_dwordx4 v[196:199], v[164:165], off offset:512
	v_add_co_u32_e32 v164, vcc, 0x20000, v150
	s_nop 1
	v_addc_co_u32_e32 v165, vcc, 0, v151, vcc
	global_load_dwordx4 v[236:239], v[164:165], off offset:16
	global_load_dwordx4 v[240:243], v[164:165], off
	global_load_dwordx4 v[244:247], v[164:165], off offset:528
	global_load_dwordx4 v[248:251], v[164:165], off offset:512
	v_add_co_u32_e32 v164, vcc, 0x30000, v150
	s_nop 1
	v_addc_co_u32_e32 v165, vcc, 0, v151, vcc
	global_load_dwordx4 v[200:203], v[164:165], off offset:16
	global_load_dwordx4 v[204:207], v[164:165], off
	global_load_dwordx4 v[212:215], v[164:165], off offset:528
	global_load_dwordx4 v[146:149], v[164:165], off offset:512
	s_waitcnt vmcnt(8)
	v_pk_fma_f32 v[156:157], v[142:143], v[134:135], v[156:157]
	v_pk_fma_f32 v[158:159], v[144:145], v[136:137], v[158:159]
	v_pk_fma_f32 v[152:153], v[138:139], v[130:131], v[152:153]
	v_pk_fma_f32 v[154:155], v[140:141], v[132:133], v[154:155]
	v_cvt_pk_bf16_f32 v156, v156, v157
	v_cvt_pk_bf16_f32 v157, v158, v159
	v_cvt_pk_bf16_f32 v158, v152, v153
	v_cvt_pk_bf16_f32 v159, v154, v155
	global_store_dwordx4 v[208:209], v[156:159], off
	v_pk_fma_f32 v[176:177], v[118:119], v[126:127], v[176:177]
	v_pk_fma_f32 v[178:179], v[120:121], v[128:129], v[178:179]
	v_pk_fma_f32 v[160:161], v[114:115], v[122:123], v[160:161]
	v_pk_fma_f32 v[162:163], v[116:117], v[124:125], v[162:163]
	v_cvt_pk_bf16_f32 v176, v176, v177
	v_cvt_pk_bf16_f32 v177, v178, v179
	v_cvt_pk_bf16_f32 v178, v160, v161
	v_cvt_pk_bf16_f32 v179, v162, v163
	global_store_dwordx4 v[208:209], v[176:179], off offset:256
	v_add_co_u32_e32 v164, vcc, 0x8000, v208
	s_nop 1
	v_addc_co_u32_e32 v165, vcc, 0, v209, vcc
	v_pk_fma_f32 v[184:185], v[110:111], v[134:135], v[184:185]
	v_pk_fma_f32 v[186:187], v[112:113], v[136:137], v[186:187]
	v_pk_fma_f32 v[180:181], v[106:107], v[130:131], v[180:181]
	v_pk_fma_f32 v[182:183], v[108:109], v[132:133], v[182:183]
	v_cvt_pk_bf16_f32 v184, v184, v185
	v_cvt_pk_bf16_f32 v185, v186, v187
	v_cvt_pk_bf16_f32 v186, v180, v181
	v_cvt_pk_bf16_f32 v187, v182, v183
	global_store_dwordx4 v[164:165], v[184:187], off
	v_pk_fma_f32 v[196:197], v[102:103], v[126:127], v[196:197]
	v_pk_fma_f32 v[198:199], v[104:105], v[128:129], v[198:199]
	v_pk_fma_f32 v[192:193], v[98:99], v[122:123], v[192:193]
	v_pk_fma_f32 v[194:195], v[100:101], v[124:125], v[194:195]
	v_cvt_pk_bf16_f32 v196, v196, v197
	v_cvt_pk_bf16_f32 v197, v198, v199
	v_cvt_pk_bf16_f32 v198, v192, v193
	v_cvt_pk_bf16_f32 v199, v194, v195
	global_store_dwordx4 v[164:165], v[196:199], off offset:256
	v_add_co_u32_e32 v164, vcc, 0x80000, v150
	s_nop 1
	v_addc_co_u32_e32 v165, vcc, 0, v151, vcc
	global_load_dwordx4 v[152:155], v[164:165], off offset:16
	global_load_dwordx4 v[156:159], v[164:165], off
	global_load_dwordx4 v[160:163], v[164:165], off offset:528
	global_load_dwordx4 v[176:179], v[164:165], off offset:512
	v_add_co_u32_e32 v164, vcc, 0x90000, v150
	s_nop 1
	v_addc_co_u32_e32 v165, vcc, 0, v151, vcc
	global_load_dwordx4 v[180:183], v[164:165], off offset:16
	global_load_dwordx4 v[184:187], v[164:165], off
	global_load_dwordx4 v[192:195], v[164:165], off offset:528
	global_load_dwordx4 v[196:199], v[164:165], off offset:512
	s_waitcnt vmcnt(12)
	v_add_co_u32_e32 v164, vcc, 0x10000, v208
	s_nop 1
	v_addc_co_u32_e32 v165, vcc, 0, v209, vcc
	v_pk_fma_f32 v[240:241], v[94:95], v[134:135], v[240:241]
	v_pk_fma_f32 v[242:243], v[96:97], v[136:137], v[242:243]
	v_pk_fma_f32 v[236:237], v[90:91], v[130:131], v[236:237]
	v_pk_fma_f32 v[238:239], v[92:93], v[132:133], v[238:239]
	v_cvt_pk_bf16_f32 v240, v240, v241
	v_cvt_pk_bf16_f32 v241, v242, v243
	v_cvt_pk_bf16_f32 v242, v236, v237
	v_cvt_pk_bf16_f32 v243, v238, v239
	global_store_dwordx4 v[164:165], v[240:243], off
	v_pk_fma_f32 v[248:249], v[86:87], v[126:127], v[248:249]
	v_pk_fma_f32 v[250:251], v[88:89], v[128:129], v[250:251]
	v_pk_fma_f32 v[244:245], v[82:83], v[122:123], v[244:245]
	v_pk_fma_f32 v[246:247], v[84:85], v[124:125], v[246:247]
	v_cvt_pk_bf16_f32 v248, v248, v249
	v_cvt_pk_bf16_f32 v249, v250, v251
	v_cvt_pk_bf16_f32 v250, v244, v245
	v_cvt_pk_bf16_f32 v251, v246, v247
	global_store_dwordx4 v[164:165], v[248:251], off offset:256
	v_add_co_u32_e32 v164, vcc, 0x18000, v208
	s_nop 1
	v_addc_co_u32_e32 v165, vcc, 0, v209, vcc
	v_pk_fma_f32 v[204:205], v[78:79], v[134:135], v[204:205]
	v_pk_fma_f32 v[206:207], v[80:81], v[136:137], v[206:207]
	v_pk_fma_f32 v[200:201], v[74:75], v[130:131], v[200:201]
	v_pk_fma_f32 v[202:203], v[76:77], v[132:133], v[202:203]
	v_cvt_pk_bf16_f32 v204, v204, v205
	v_cvt_pk_bf16_f32 v205, v206, v207
	v_cvt_pk_bf16_f32 v206, v200, v201
	v_cvt_pk_bf16_f32 v207, v202, v203
	global_store_dwordx4 v[164:165], v[204:207], off
	v_pk_fma_f32 v[146:147], v[70:71], v[126:127], v[146:147]
	v_pk_fma_f32 v[148:149], v[72:73], v[128:129], v[148:149]
	v_pk_fma_f32 v[212:213], v[66:67], v[122:123], v[212:213]
	v_pk_fma_f32 v[214:215], v[68:69], v[124:125], v[214:215]
	v_cvt_pk_bf16_f32 v146, v146, v147
	v_cvt_pk_bf16_f32 v147, v148, v149
	v_cvt_pk_bf16_f32 v148, v212, v213
	v_cvt_pk_bf16_f32 v149, v214, v215
	global_store_dwordx4 v[164:165], v[146:149], off offset:256
	v_add_co_u32_e32 v164, vcc, 0xa0000, v150
	s_nop 1
	v_addc_co_u32_e32 v165, vcc, 0, v151, vcc
	global_load_dwordx4 v[236:239], v[164:165], off offset:16
	global_load_dwordx4 v[240:243], v[164:165], off
	global_load_dwordx4 v[244:247], v[164:165], off offset:528
	global_load_dwordx4 v[248:251], v[164:165], off offset:512
	v_add_co_u32_e32 v164, vcc, 0xb0000, v150
	s_nop 1
	v_addc_co_u32_e32 v165, vcc, 0, v151, vcc
	global_load_dwordx4 v[200:203], v[164:165], off offset:16
	global_load_dwordx4 v[204:207], v[164:165], off
	global_load_dwordx4 v[212:215], v[164:165], off offset:528
	global_load_dwordx4 v[146:149], v[164:165], off offset:512
	s_waitcnt vmcnt(12)
	v_add_co_u32_e32 v164, vcc, 0x40000, v208
	s_nop 1
	v_addc_co_u32_e32 v165, vcc, 0, v209, vcc
	v_pk_fma_f32 v[156:157], v[62:63], v[134:135], v[156:157]
	v_pk_fma_f32 v[158:159], v[64:65], v[136:137], v[158:159]
	v_pk_fma_f32 v[152:153], v[58:59], v[130:131], v[152:153]
	v_pk_fma_f32 v[154:155], v[60:61], v[132:133], v[154:155]
	v_cvt_pk_bf16_f32 v156, v156, v157
	v_cvt_pk_bf16_f32 v157, v158, v159
	v_cvt_pk_bf16_f32 v158, v152, v153
	v_cvt_pk_bf16_f32 v159, v154, v155
	global_store_dwordx4 v[164:165], v[156:159], off
	v_pk_fma_f32 v[176:177], v[54:55], v[126:127], v[176:177]
	v_pk_fma_f32 v[178:179], v[56:57], v[128:129], v[178:179]
	v_pk_fma_f32 v[160:161], v[50:51], v[122:123], v[160:161]
	v_pk_fma_f32 v[162:163], v[52:53], v[124:125], v[162:163]
	v_cvt_pk_bf16_f32 v176, v176, v177
	v_cvt_pk_bf16_f32 v177, v178, v179
	v_cvt_pk_bf16_f32 v178, v160, v161
	v_cvt_pk_bf16_f32 v179, v162, v163
	global_store_dwordx4 v[164:165], v[176:179], off offset:256
	v_add_co_u32_e32 v164, vcc, 0x48000, v208
	s_nop 1
	v_addc_co_u32_e32 v165, vcc, 0, v209, vcc
	v_pk_fma_f32 v[184:185], v[46:47], v[134:135], v[184:185]
	v_pk_fma_f32 v[186:187], v[48:49], v[136:137], v[186:187]
	v_pk_fma_f32 v[180:181], v[42:43], v[130:131], v[180:181]
	v_pk_fma_f32 v[182:183], v[44:45], v[132:133], v[182:183]
	v_cvt_pk_bf16_f32 v184, v184, v185
	v_cvt_pk_bf16_f32 v185, v186, v187
	v_cvt_pk_bf16_f32 v186, v180, v181
	v_cvt_pk_bf16_f32 v187, v182, v183
	global_store_dwordx4 v[164:165], v[184:187], off
	v_pk_fma_f32 v[196:197], v[38:39], v[126:127], v[196:197]
	v_pk_fma_f32 v[198:199], v[40:41], v[128:129], v[198:199]
	v_pk_fma_f32 v[192:193], v[34:35], v[122:123], v[192:193]
	v_pk_fma_f32 v[194:195], v[36:37], v[124:125], v[194:195]
	v_cvt_pk_bf16_f32 v196, v196, v197
	v_cvt_pk_bf16_f32 v197, v198, v199
	v_cvt_pk_bf16_f32 v198, v192, v193
	v_cvt_pk_bf16_f32 v199, v194, v195
	global_store_dwordx4 v[164:165], v[196:199], off offset:256
	s_waitcnt vmcnt(4)
	v_add_co_u32_e32 v164, vcc, 0x50000, v208
	s_nop 1
	v_addc_co_u32_e32 v165, vcc, 0, v209, vcc
	v_pk_fma_f32 v[240:241], v[30:31], v[134:135], v[240:241]
	v_pk_fma_f32 v[242:243], v[32:33], v[136:137], v[242:243]
	v_pk_fma_f32 v[236:237], v[26:27], v[130:131], v[236:237]
	v_pk_fma_f32 v[238:239], v[28:29], v[132:133], v[238:239]
	v_cvt_pk_bf16_f32 v240, v240, v241
	v_cvt_pk_bf16_f32 v241, v242, v243
	v_cvt_pk_bf16_f32 v242, v236, v237
	v_cvt_pk_bf16_f32 v243, v238, v239
	global_store_dwordx4 v[164:165], v[240:243], off
	v_pk_fma_f32 v[248:249], v[22:23], v[126:127], v[248:249]
	v_pk_fma_f32 v[250:251], v[24:25], v[128:129], v[250:251]
	v_pk_fma_f32 v[244:245], v[18:19], v[122:123], v[244:245]
	v_pk_fma_f32 v[246:247], v[20:21], v[124:125], v[246:247]
	v_cvt_pk_bf16_f32 v248, v248, v249
	v_cvt_pk_bf16_f32 v249, v250, v251
	v_cvt_pk_bf16_f32 v250, v244, v245
	v_cvt_pk_bf16_f32 v251, v246, v247
	global_store_dwordx4 v[164:165], v[248:251], off offset:256
	v_add_co_u32_e32 v164, vcc, 0x58000, v208
	s_nop 1
	v_addc_co_u32_e32 v165, vcc, 0, v209, vcc
	v_pk_fma_f32 v[204:205], v[14:15], v[134:135], v[204:205]
	v_pk_fma_f32 v[206:207], v[16:17], v[136:137], v[206:207]
	v_pk_fma_f32 v[200:201], v[10:11], v[130:131], v[200:201]
	v_pk_fma_f32 v[202:203], v[12:13], v[132:133], v[202:203]
	v_cvt_pk_bf16_f32 v204, v204, v205
	v_cvt_pk_bf16_f32 v205, v206, v207
	v_cvt_pk_bf16_f32 v206, v200, v201
	v_cvt_pk_bf16_f32 v207, v202, v203
	global_store_dwordx4 v[164:165], v[204:207], off
	v_pk_fma_f32 v[146:147], v[6:7], v[126:127], v[146:147]
	v_pk_fma_f32 v[148:149], v[8:9], v[128:129], v[148:149]
	v_pk_fma_f32 v[212:213], v[2:3], v[122:123], v[212:213]
	v_pk_fma_f32 v[214:215], v[4:5], v[124:125], v[214:215]
	v_cvt_pk_bf16_f32 v146, v146, v147
	v_cvt_pk_bf16_f32 v147, v148, v149
	v_cvt_pk_bf16_f32 v148, v212, v213
	v_cvt_pk_bf16_f32 v149, v214, v215
	global_store_dwordx4 v[164:165], v[146:149], off offset:256
	s_mov_b64 s[16:17], 0
